# same batched trailing-window loads also on the last-panel (tail workgroup) row phase
# baseline (speedup 1.0000x reference)
; __device__ __forceinline__ void unpack8(const u32x4 w, float* v) { v[0] = bflo(w.x); v[1] = bfhi(w.x); v[2] = bflo(w.y); v[3] = bfhi(w.y); v[4] = bflo(w.z); v[5] = bfhi(w.z); v[6] = bflo(w.w); v[7] = bfhi(w.w); }
; __device__ __forceinline__ void row_res(KP kp, int gpost_in, int layer, bool has_next, int wid0, int row0, int row1, int b0, int nb, int tailp, bool pooled) {
;     ...
;                 else if (pooled) { const int t = row % LL, win = 2 << (c * 2 + (lane >> 5)), cnt = (t + 1) < win ? (t + 1) : win; const bf16* zp = MX + (size_t)row * DM + c * 512 + lane * 8;
;                     float z0[8], sum[8]; unpack8(*(const u32x4*)zp, z0);
; #pragma unroll
;                     for (int j = 0; j < 8; ++j) sum[j] = z0[j];
;                     for (int d = 1; d < cnt; ++d) { float zd[8]; unpack8(*(const u32x4*)(zp - (size_t)d * DM), zd);
; #pragma unroll
;                         for (int j = 0; j < 8; ++j) sum[j] += zd[j]; }
;                     const float inv = 1.0f / (float)cnt;
; #pragma unroll
;                     for (int j = 0; j < 8; ++j) m[r][c][j] = sum[j] * inv - z0[j]; }
.LBB0_867:
	s_andn2_b64 vcc, exec, s[4:5]
	s_cbranch_vccnz .LBB0_873
	v_min_i32_e32 v17, v16, v1
	v_cmp_lt_i32_e32 vcc, 1, v17
	v_mov_b64_e32 v[12:13], v[22:23]
	v_mov_b64_e32 v[10:11], v[24:25]
	v_mov_b64_e32 v[8:9], v[26:27]
	v_mov_b64_e32 v[4:5], v[28:29]
	s_and_saveexec_b64 s[4:5], vcc
	s_cbranch_execz .LBB0_872
	v_add_u32_e32 v18, -1, v17
	s_mov_b64 s[14:15], 0
	v_mov_b64_e32 v[14:15], v[50:51]
	v_mov_b64_e32 v[4:5], v[28:29]
	v_mov_b64_e32 v[8:9], v[26:27]
	v_mov_b64_e32 v[10:11], v[24:25]
	v_mov_b64_e32 v[12:13], v[22:23]
	s_mov_b64 s[14:15], exec
	global_load_dwordx4 v[174:177], v[14:15], off
	v_lshl_add_u64 v[14:15], v[14:15], 0, s[54:55]
	v_cmp_le_u32_e32 vcc, 2, v18
	s_and_b64 exec, s[14:15], vcc
	s_cbranch_execz .Lpl_e_iss
	global_load_dwordx4 v[178:181], v[14:15], off
	v_lshl_add_u64 v[14:15], v[14:15], 0, s[54:55]
	v_cmp_le_u32_e32 vcc, 3, v18
	s_and_b64 exec, s[14:15], vcc
	s_cbranch_execz .Lpl_e_iss
	global_load_dwordx4 v[182:185], v[14:15], off
.Lpl_e_iss:
	s_mov_b64 exec, s[14:15]
	s_waitcnt vmcnt(0)
	v_lshlrev_b32_e32 v234, 16, v174
	v_and_b32_e32 v235, 0xffff0000, v174
	v_pk_add_f32 v[12:13], v[12:13], v[234:235]
	v_lshlrev_b32_e32 v234, 16, v175
	v_and_b32_e32 v235, 0xffff0000, v175
	v_pk_add_f32 v[10:11], v[10:11], v[234:235]
	v_lshlrev_b32_e32 v234, 16, v176
	v_and_b32_e32 v235, 0xffff0000, v176
	v_pk_add_f32 v[8:9], v[8:9], v[234:235]
	v_lshlrev_b32_e32 v234, 16, v177
	v_and_b32_e32 v235, 0xffff0000, v177
	v_pk_add_f32 v[4:5], v[4:5], v[234:235]
	v_cmp_le_u32_e32 vcc, 2, v18
	s_and_b64 exec, s[14:15], vcc
	s_cbranch_execz .Lpl_e_done
	v_lshlrev_b32_e32 v234, 16, v178
	v_and_b32_e32 v235, 0xffff0000, v178
	v_pk_add_f32 v[12:13], v[12:13], v[234:235]
	v_lshlrev_b32_e32 v234, 16, v179
	v_and_b32_e32 v235, 0xffff0000, v179
	v_pk_add_f32 v[10:11], v[10:11], v[234:235]
	v_lshlrev_b32_e32 v234, 16, v180
	v_and_b32_e32 v235, 0xffff0000, v180
	v_pk_add_f32 v[8:9], v[8:9], v[234:235]
	v_lshlrev_b32_e32 v234, 16, v181
	v_and_b32_e32 v235, 0xffff0000, v181
	v_pk_add_f32 v[4:5], v[4:5], v[234:235]
	v_cmp_le_u32_e32 vcc, 3, v18
	s_and_b64 exec, s[14:15], vcc
	s_cbranch_execz .Lpl_e_done
	v_lshlrev_b32_e32 v234, 16, v182
	v_and_b32_e32 v235, 0xffff0000, v182
	v_pk_add_f32 v[12:13], v[12:13], v[234:235]
	v_lshlrev_b32_e32 v234, 16, v183
	v_and_b32_e32 v235, 0xffff0000, v183
	v_pk_add_f32 v[10:11], v[10:11], v[234:235]
	v_lshlrev_b32_e32 v234, 16, v184
	v_and_b32_e32 v235, 0xffff0000, v184
	v_pk_add_f32 v[8:9], v[8:9], v[234:235]
	v_lshlrev_b32_e32 v234, 16, v185
	v_and_b32_e32 v235, 0xffff0000, v185
	v_pk_add_f32 v[4:5], v[4:5], v[234:235]
.Lpl_e_done:
	s_mov_b64 exec, s[14:15]
.LBB0_872:
	s_or_b64 exec, exec, s[4:5]
	v_cvt_f32_i32_e32 v14, v17
	v_div_scale_f32 v15, s[4:5], v14, v14, 1.0
	v_rcp_f32_e32 v17, v15
	v_div_scale_f32 v18, vcc, 1.0, v14, 1.0
	v_fma_f32 v19, -v15, v17, 1.0
	v_fmac_f32_e32 v17, v19, v17
	v_mul_f32_e32 v19, v18, v17
	v_fma_f32 v20, -v15, v19, v18
	v_fmac_f32_e32 v19, v20, v17
	v_fma_f32 v15, -v15, v19, v18
	v_div_fmas_f32 v15, v15, v17, v19
	v_div_fixup_f32 v14, v15, v14, 1.0
	v_pk_fma_f32 v[22:23], v[14:15], v[12:13], v[22:23] op_sel_hi:[0,1,1] neg_lo:[0,0,1] neg_hi:[0,0,1]
	v_pk_fma_f32 v[24:25], v[14:15], v[10:11], v[24:25] op_sel_hi:[0,1,1] neg_lo:[0,0,1] neg_hi:[0,0,1]
	v_pk_fma_f32 v[26:27], v[14:15], v[8:9], v[26:27] op_sel_hi:[0,1,1] neg_lo:[0,0,1] neg_hi:[0,0,1]
	v_pk_fma_f32 v[28:29], v[14:15], v[4:5], v[28:29] op_sel_hi:[0,1,1] neg_lo:[0,0,1] neg_hi:[0,0,1]

; __device__ __forceinline__ void unpack8(const u32x4 w, float* v) { v[0] = bflo(w.x); v[1] = bfhi(w.x); v[2] = bflo(w.y); v[3] = bfhi(w.y); v[4] = bflo(w.z); v[5] = bfhi(w.z); v[6] = bflo(w.w); v[7] = bfhi(w.w); }
; __device__ __forceinline__ void row_res(KP kp, int gpost_in, int layer, bool has_next, int wid0, int row0, int row1, int b0, int nb, int tailp, bool pooled) {
;     ...
;                 else if (pooled) { const int t = row % LL, win = 2 << (c * 2 + (lane >> 5)), cnt = (t + 1) < win ? (t + 1) : win; const bf16* zp = MX + (size_t)row * DM + c * 512 + lane * 8;
;                     float z0[8], sum[8]; unpack8(*(const u32x4*)zp, z0);
; #pragma unroll
;                     for (int j = 0; j < 8; ++j) sum[j] = z0[j];
;                     for (int d = 1; d < cnt; ++d) { float zd[8]; unpack8(*(const u32x4*)(zp - (size_t)d * DM), zd);
; #pragma unroll
;                         for (int j = 0; j < 8; ++j) sum[j] += zd[j]; }
;                     const float inv = 1.0f / (float)cnt;
; #pragma unroll
;                     for (int j = 0; j < 8; ++j) m[r][c][j] = sum[j] * inv - z0[j]; }
.LBB0_879:
	s_andn2_b64 vcc, exec, s[14:15]
	s_cbranch_vccnz .LBB0_885
	v_min_i32_e32 v20, v16, v41
	v_cmp_lt_i32_e32 vcc, 1, v20
	v_mov_b64_e32 v[16:17], v[30:31]
	v_mov_b64_e32 v[14:15], v[32:33]
	v_mov_b64_e32 v[12:13], v[34:35]
	v_mov_b64_e32 v[6:7], v[36:37]
	s_and_saveexec_b64 s[14:15], vcc
	s_cbranch_execz .LBB0_884
	v_add_u32_e32 v21, -1, v20
	s_mov_b64 s[46:47], 0
	v_mov_b64_e32 v[18:19], v[52:53]
	v_mov_b64_e32 v[6:7], v[36:37]
	v_mov_b64_e32 v[12:13], v[34:35]
	v_mov_b64_e32 v[14:15], v[32:33]
	v_mov_b64_e32 v[16:17], v[30:31]
	s_mov_b64 s[46:47], exec
	global_load_dwordx4 v[174:177], v[18:19], off
	v_lshl_add_u64 v[18:19], v[18:19], 0, s[54:55]
	v_cmp_le_u32_e32 vcc, 2, v21
	s_and_b64 exec, s[46:47], vcc
	s_cbranch_execz .Lpl_f_iss
	global_load_dwordx4 v[178:181], v[18:19], off
	v_lshl_add_u64 v[18:19], v[18:19], 0, s[54:55]
	v_cmp_le_u32_e32 vcc, 3, v21
	s_and_b64 exec, s[46:47], vcc
	s_cbranch_execz .Lpl_f_iss
	global_load_dwordx4 v[182:185], v[18:19], off
	v_lshl_add_u64 v[18:19], v[18:19], 0, s[54:55]
	v_cmp_le_u32_e32 vcc, 4, v21
	s_and_b64 exec, s[46:47], vcc
	s_cbranch_execz .Lpl_f_iss
	global_load_dwordx4 v[186:189], v[18:19], off
	v_lshl_add_u64 v[18:19], v[18:19], 0, s[54:55]
	v_cmp_le_u32_e32 vcc, 5, v21
	s_and_b64 exec, s[46:47], vcc
	s_cbranch_execz .Lpl_f_iss
	global_load_dwordx4 v[190:193], v[18:19], off
	v_lshl_add_u64 v[18:19], v[18:19], 0, s[54:55]
	v_cmp_le_u32_e32 vcc, 6, v21
	s_and_b64 exec, s[46:47], vcc
	s_cbranch_execz .Lpl_f_iss
	global_load_dwordx4 v[194:197], v[18:19], off
	v_lshl_add_u64 v[18:19], v[18:19], 0, s[54:55]
	v_cmp_le_u32_e32 vcc, 7, v21
	s_and_b64 exec, s[46:47], vcc
	s_cbranch_execz .Lpl_f_iss
	global_load_dwordx4 v[198:201], v[18:19], off
	v_lshl_add_u64 v[18:19], v[18:19], 0, s[54:55]
	v_cmp_le_u32_e32 vcc, 8, v21
	s_and_b64 exec, s[46:47], vcc
	s_cbranch_execz .Lpl_f_iss
	global_load_dwordx4 v[202:205], v[18:19], off
	v_lshl_add_u64 v[18:19], v[18:19], 0, s[54:55]
	v_cmp_le_u32_e32 vcc, 9, v21
	s_and_b64 exec, s[46:47], vcc
	s_cbranch_execz .Lpl_f_iss
	global_load_dwordx4 v[206:209], v[18:19], off
	v_lshl_add_u64 v[18:19], v[18:19], 0, s[54:55]
	v_cmp_le_u32_e32 vcc, 10, v21
	s_and_b64 exec, s[46:47], vcc
	s_cbranch_execz .Lpl_f_iss
	global_load_dwordx4 v[210:213], v[18:19], off
	v_lshl_add_u64 v[18:19], v[18:19], 0, s[54:55]
	v_cmp_le_u32_e32 vcc, 11, v21
	s_and_b64 exec, s[46:47], vcc
	s_cbranch_execz .Lpl_f_iss
	global_load_dwordx4 v[214:217], v[18:19], off
	v_lshl_add_u64 v[18:19], v[18:19], 0, s[54:55]
	v_cmp_le_u32_e32 vcc, 12, v21
	s_and_b64 exec, s[46:47], vcc
	s_cbranch_execz .Lpl_f_iss
	global_load_dwordx4 v[218:221], v[18:19], off
	v_lshl_add_u64 v[18:19], v[18:19], 0, s[54:55]
	v_cmp_le_u32_e32 vcc, 13, v21
	s_and_b64 exec, s[46:47], vcc
	s_cbranch_execz .Lpl_f_iss
	global_load_dwordx4 v[222:225], v[18:19], off
	v_lshl_add_u64 v[18:19], v[18:19], 0, s[54:55]
	v_cmp_le_u32_e32 vcc, 14, v21
	s_and_b64 exec, s[46:47], vcc
	s_cbranch_execz .Lpl_f_iss
	global_load_dwordx4 v[226:229], v[18:19], off
	v_lshl_add_u64 v[18:19], v[18:19], 0, s[54:55]
	v_cmp_le_u32_e32 vcc, 15, v21
	s_and_b64 exec, s[46:47], vcc
	s_cbranch_execz .Lpl_f_iss
	global_load_dwordx4 v[230:233], v[18:19], off
.Lpl_f_iss:
	s_mov_b64 exec, s[46:47]
	s_waitcnt vmcnt(0)
	v_lshlrev_b32_e32 v234, 16, v174
	v_and_b32_e32 v235, 0xffff0000, v174
	v_pk_add_f32 v[16:17], v[16:17], v[234:235]
	v_lshlrev_b32_e32 v234, 16, v175
	v_and_b32_e32 v235, 0xffff0000, v175
	v_pk_add_f32 v[14:15], v[14:15], v[234:235]
	v_lshlrev_b32_e32 v234, 16, v176
	v_and_b32_e32 v235, 0xffff0000, v176
	v_pk_add_f32 v[12:13], v[12:13], v[234:235]
	v_lshlrev_b32_e32 v234, 16, v177
	v_and_b32_e32 v235, 0xffff0000, v177
	v_pk_add_f32 v[6:7], v[6:7], v[234:235]
	v_cmp_le_u32_e32 vcc, 2, v21
	s_and_b64 exec, s[46:47], vcc
	s_cbranch_execz .Lpl_f_done
	v_lshlrev_b32_e32 v234, 16, v178
	v_and_b32_e32 v235, 0xffff0000, v178
	v_pk_add_f32 v[16:17], v[16:17], v[234:235]
	v_lshlrev_b32_e32 v234, 16, v179
	v_and_b32_e32 v235, 0xffff0000, v179
	v_pk_add_f32 v[14:15], v[14:15], v[234:235]
	v_lshlrev_b32_e32 v234, 16, v180
	v_and_b32_e32 v235, 0xffff0000, v180
	v_pk_add_f32 v[12:13], v[12:13], v[234:235]
	v_lshlrev_b32_e32 v234, 16, v181
	v_and_b32_e32 v235, 0xffff0000, v181
	v_pk_add_f32 v[6:7], v[6:7], v[234:235]
	v_cmp_le_u32_e32 vcc, 3, v21
	s_and_b64 exec, s[46:47], vcc
	s_cbranch_execz .Lpl_f_done
	v_lshlrev_b32_e32 v234, 16, v182
	v_and_b32_e32 v235, 0xffff0000, v182
	v_pk_add_f32 v[16:17], v[16:17], v[234:235]
	v_lshlrev_b32_e32 v234, 16, v183
	v_and_b32_e32 v235, 0xffff0000, v183
	v_pk_add_f32 v[14:15], v[14:15], v[234:235]
	v_lshlrev_b32_e32 v234, 16, v184
	v_and_b32_e32 v235, 0xffff0000, v184
	v_pk_add_f32 v[12:13], v[12:13], v[234:235]
	v_lshlrev_b32_e32 v234, 16, v185
	v_and_b32_e32 v235, 0xffff0000, v185
	v_pk_add_f32 v[6:7], v[6:7], v[234:235]
	v_cmp_le_u32_e32 vcc, 4, v21
	s_and_b64 exec, s[46:47], vcc
	s_cbranch_execz .Lpl_f_done
	v_lshlrev_b32_e32 v234, 16, v186
	v_and_b32_e32 v235, 0xffff0000, v186
	v_pk_add_f32 v[16:17], v[16:17], v[234:235]
	v_lshlrev_b32_e32 v234, 16, v187
	v_and_b32_e32 v235, 0xffff0000, v187
	v_pk_add_f32 v[14:15], v[14:15], v[234:235]
	v_lshlrev_b32_e32 v234, 16, v188
	v_and_b32_e32 v235, 0xffff0000, v188
	v_pk_add_f32 v[12:13], v[12:13], v[234:235]
	v_lshlrev_b32_e32 v234, 16, v189
	v_and_b32_e32 v235, 0xffff0000, v189
	v_pk_add_f32 v[6:7], v[6:7], v[234:235]
	v_cmp_le_u32_e32 vcc, 5, v21
	s_and_b64 exec, s[46:47], vcc
	s_cbranch_execz .Lpl_f_done
; __device__ __forceinline__ void unpack8(const u32x4 w, float* v) { v[0] = bflo(w.x); v[1] = bfhi(w.x); v[2] = bflo(w.y); v[3] = bfhi(w.y); v[4] = bflo(w.z); v[5] = bfhi(w.z); v[6] = bflo(w.w); v[7] = bfhi(w.w); }
; __device__ __forceinline__ void row_res(KP kp, int gpost_in, int layer, bool has_next, int wid0, int row0, int row1, int b0, int nb, int tailp, bool pooled) {
;     ...
;                 else if (pooled) { const int t = row % LL, win = 2 << (c * 2 + (lane >> 5)), cnt = (t + 1) < win ? (t + 1) : win; const bf16* zp = MX + (size_t)row * DM + c * 512 + lane * 8;
;                     float z0[8], sum[8]; unpack8(*(const u32x4*)zp, z0);
; #pragma unroll
;                     for (int j = 0; j < 8; ++j) sum[j] = z0[j];
;                     for (int d = 1; d < cnt; ++d) { float zd[8]; unpack8(*(const u32x4*)(zp - (size_t)d * DM), zd);
; #pragma unroll
;                         for (int j = 0; j < 8; ++j) sum[j] += zd[j]; }
;                     const float inv = 1.0f / (float)cnt;
; #pragma unroll
;                     for (int j = 0; j < 8; ++j) m[r][c][j] = sum[j] * inv - z0[j]; }
	v_lshlrev_b32_e32 v234, 16, v190
	v_and_b32_e32 v235, 0xffff0000, v190
	v_pk_add_f32 v[16:17], v[16:17], v[234:235]
	v_lshlrev_b32_e32 v234, 16, v191
	v_and_b32_e32 v235, 0xffff0000, v191
	v_pk_add_f32 v[14:15], v[14:15], v[234:235]
	v_lshlrev_b32_e32 v234, 16, v192
	v_and_b32_e32 v235, 0xffff0000, v192
	v_pk_add_f32 v[12:13], v[12:13], v[234:235]
	v_lshlrev_b32_e32 v234, 16, v193
	v_and_b32_e32 v235, 0xffff0000, v193
	v_pk_add_f32 v[6:7], v[6:7], v[234:235]
	v_cmp_le_u32_e32 vcc, 6, v21
	s_and_b64 exec, s[46:47], vcc
	s_cbranch_execz .Lpl_f_done
	v_lshlrev_b32_e32 v234, 16, v194
	v_and_b32_e32 v235, 0xffff0000, v194
	v_pk_add_f32 v[16:17], v[16:17], v[234:235]
	v_lshlrev_b32_e32 v234, 16, v195
	v_and_b32_e32 v235, 0xffff0000, v195
	v_pk_add_f32 v[14:15], v[14:15], v[234:235]
	v_lshlrev_b32_e32 v234, 16, v196
	v_and_b32_e32 v235, 0xffff0000, v196
	v_pk_add_f32 v[12:13], v[12:13], v[234:235]
	v_lshlrev_b32_e32 v234, 16, v197
	v_and_b32_e32 v235, 0xffff0000, v197
	v_pk_add_f32 v[6:7], v[6:7], v[234:235]
	v_cmp_le_u32_e32 vcc, 7, v21
	s_and_b64 exec, s[46:47], vcc
	s_cbranch_execz .Lpl_f_done
	v_lshlrev_b32_e32 v234, 16, v198
	v_and_b32_e32 v235, 0xffff0000, v198
	v_pk_add_f32 v[16:17], v[16:17], v[234:235]
	v_lshlrev_b32_e32 v234, 16, v199
	v_and_b32_e32 v235, 0xffff0000, v199
	v_pk_add_f32 v[14:15], v[14:15], v[234:235]
	v_lshlrev_b32_e32 v234, 16, v200
	v_and_b32_e32 v235, 0xffff0000, v200
	v_pk_add_f32 v[12:13], v[12:13], v[234:235]
	v_lshlrev_b32_e32 v234, 16, v201
	v_and_b32_e32 v235, 0xffff0000, v201
	v_pk_add_f32 v[6:7], v[6:7], v[234:235]
	v_cmp_le_u32_e32 vcc, 8, v21
	s_and_b64 exec, s[46:47], vcc
	s_cbranch_execz .Lpl_f_done
	v_lshlrev_b32_e32 v234, 16, v202
	v_and_b32_e32 v235, 0xffff0000, v202
	v_pk_add_f32 v[16:17], v[16:17], v[234:235]
	v_lshlrev_b32_e32 v234, 16, v203
	v_and_b32_e32 v235, 0xffff0000, v203
	v_pk_add_f32 v[14:15], v[14:15], v[234:235]
	v_lshlrev_b32_e32 v234, 16, v204
	v_and_b32_e32 v235, 0xffff0000, v204
	v_pk_add_f32 v[12:13], v[12:13], v[234:235]
	v_lshlrev_b32_e32 v234, 16, v205
	v_and_b32_e32 v235, 0xffff0000, v205
	v_pk_add_f32 v[6:7], v[6:7], v[234:235]
	v_cmp_le_u32_e32 vcc, 9, v21
	s_and_b64 exec, s[46:47], vcc
	s_cbranch_execz .Lpl_f_done
	v_lshlrev_b32_e32 v234, 16, v206
	v_and_b32_e32 v235, 0xffff0000, v206
	v_pk_add_f32 v[16:17], v[16:17], v[234:235]
	v_lshlrev_b32_e32 v234, 16, v207
	v_and_b32_e32 v235, 0xffff0000, v207
	v_pk_add_f32 v[14:15], v[14:15], v[234:235]
	v_lshlrev_b32_e32 v234, 16, v208
	v_and_b32_e32 v235, 0xffff0000, v208
	v_pk_add_f32 v[12:13], v[12:13], v[234:235]
	v_lshlrev_b32_e32 v234, 16, v209
	v_and_b32_e32 v235, 0xffff0000, v209
	v_pk_add_f32 v[6:7], v[6:7], v[234:235]
	v_cmp_le_u32_e32 vcc, 10, v21
	s_and_b64 exec, s[46:47], vcc
	s_cbranch_execz .Lpl_f_done
	v_lshlrev_b32_e32 v234, 16, v210
	v_and_b32_e32 v235, 0xffff0000, v210
	v_pk_add_f32 v[16:17], v[16:17], v[234:235]
	v_lshlrev_b32_e32 v234, 16, v211
	v_and_b32_e32 v235, 0xffff0000, v211
	v_pk_add_f32 v[14:15], v[14:15], v[234:235]
	v_lshlrev_b32_e32 v234, 16, v212
	v_and_b32_e32 v235, 0xffff0000, v212
	v_pk_add_f32 v[12:13], v[12:13], v[234:235]
	v_lshlrev_b32_e32 v234, 16, v213
	v_and_b32_e32 v235, 0xffff0000, v213
	v_pk_add_f32 v[6:7], v[6:7], v[234:235]
	v_cmp_le_u32_e32 vcc, 11, v21
	s_and_b64 exec, s[46:47], vcc
	s_cbranch_execz .Lpl_f_done
	v_lshlrev_b32_e32 v234, 16, v214
	v_and_b32_e32 v235, 0xffff0000, v214
	v_pk_add_f32 v[16:17], v[16:17], v[234:235]
	v_lshlrev_b32_e32 v234, 16, v215
	v_and_b32_e32 v235, 0xffff0000, v215
	v_pk_add_f32 v[14:15], v[14:15], v[234:235]
	v_lshlrev_b32_e32 v234, 16, v216
	v_and_b32_e32 v235, 0xffff0000, v216
	v_pk_add_f32 v[12:13], v[12:13], v[234:235]
	v_lshlrev_b32_e32 v234, 16, v217
	v_and_b32_e32 v235, 0xffff0000, v217
	v_pk_add_f32 v[6:7], v[6:7], v[234:235]
	v_cmp_le_u32_e32 vcc, 12, v21
	s_and_b64 exec, s[46:47], vcc
	s_cbranch_execz .Lpl_f_done
	v_lshlrev_b32_e32 v234, 16, v218
	v_and_b32_e32 v235, 0xffff0000, v218
	v_pk_add_f32 v[16:17], v[16:17], v[234:235]
	v_lshlrev_b32_e32 v234, 16, v219
	v_and_b32_e32 v235, 0xffff0000, v219
	v_pk_add_f32 v[14:15], v[14:15], v[234:235]
	v_lshlrev_b32_e32 v234, 16, v220
	v_and_b32_e32 v235, 0xffff0000, v220
	v_pk_add_f32 v[12:13], v[12:13], v[234:235]
	v_lshlrev_b32_e32 v234, 16, v221
	v_and_b32_e32 v235, 0xffff0000, v221
	v_pk_add_f32 v[6:7], v[6:7], v[234:235]
	v_cmp_le_u32_e32 vcc, 13, v21
	s_and_b64 exec, s[46:47], vcc
	s_cbranch_execz .Lpl_f_done
	v_lshlrev_b32_e32 v234, 16, v222
	v_and_b32_e32 v235, 0xffff0000, v222
	v_pk_add_f32 v[16:17], v[16:17], v[234:235]
	v_lshlrev_b32_e32 v234, 16, v223
	v_and_b32_e32 v235, 0xffff0000, v223
	v_pk_add_f32 v[14:15], v[14:15], v[234:235]
	v_lshlrev_b32_e32 v234, 16, v224
	v_and_b32_e32 v235, 0xffff0000, v224
	v_pk_add_f32 v[12:13], v[12:13], v[234:235]
	v_lshlrev_b32_e32 v234, 16, v225
	v_and_b32_e32 v235, 0xffff0000, v225
	v_pk_add_f32 v[6:7], v[6:7], v[234:235]
	v_cmp_le_u32_e32 vcc, 14, v21
	s_and_b64 exec, s[46:47], vcc
	s_cbranch_execz .Lpl_f_done
	v_lshlrev_b32_e32 v234, 16, v226
	v_and_b32_e32 v235, 0xffff0000, v226
	v_pk_add_f32 v[16:17], v[16:17], v[234:235]
	v_lshlrev_b32_e32 v234, 16, v227
	v_and_b32_e32 v235, 0xffff0000, v227
	v_pk_add_f32 v[14:15], v[14:15], v[234:235]
	v_lshlrev_b32_e32 v234, 16, v228
	v_and_b32_e32 v235, 0xffff0000, v228
	v_pk_add_f32 v[12:13], v[12:13], v[234:235]
	v_lshlrev_b32_e32 v234, 16, v229
	v_and_b32_e32 v235, 0xffff0000, v229
	v_pk_add_f32 v[6:7], v[6:7], v[234:235]
	v_cmp_le_u32_e32 vcc, 15, v21
	s_and_b64 exec, s[46:47], vcc
	s_cbranch_execz .Lpl_f_done
	v_lshlrev_b32_e32 v234, 16, v230
	v_and_b32_e32 v235, 0xffff0000, v230
	v_pk_add_f32 v[16:17], v[16:17], v[234:235]
	v_lshlrev_b32_e32 v234, 16, v231
	v_and_b32_e32 v235, 0xffff0000, v231
	v_pk_add_f32 v[14:15], v[14:15], v[234:235]
	v_lshlrev_b32_e32 v234, 16, v232
	v_and_b32_e32 v235, 0xffff0000, v232
	v_pk_add_f32 v[12:13], v[12:13], v[234:235]
	v_lshlrev_b32_e32 v234, 16, v233
	v_and_b32_e32 v235, 0xffff0000, v233
	v_pk_add_f32 v[6:7], v[6:7], v[234:235]
.Lpl_f_done:
	s_mov_b64 exec, s[46:47]

; __device__ __forceinline__ void unpack8(const u32x4 w, float* v) { v[0] = bflo(w.x); v[1] = bfhi(w.x); v[2] = bflo(w.y); v[3] = bfhi(w.y); v[4] = bflo(w.z); v[5] = bfhi(w.z); v[6] = bflo(w.w); v[7] = bfhi(w.w); }
; __device__ __forceinline__ void row_res(KP kp, int gpost_in, int layer, bool has_next, int wid0, int row0, int row1, int b0, int nb, int tailp, bool pooled) {
;     ...
;                 else if (pooled) { const int t = row % LL, win = 2 << (c * 2 + (lane >> 5)), cnt = (t + 1) < win ? (t + 1) : win; const bf16* zp = MX + (size_t)row * DM + c * 512 + lane * 8;
;                     float z0[8], sum[8]; unpack8(*(const u32x4*)zp, z0);
; #pragma unroll
;                     for (int j = 0; j < 8; ++j) sum[j] = z0[j];
;                     for (int d = 1; d < cnt; ++d) { float zd[8]; unpack8(*(const u32x4*)(zp - (size_t)d * DM), zd);
; #pragma unroll
;                         for (int j = 0; j < 8; ++j) sum[j] += zd[j]; }
;                     const float inv = 1.0f / (float)cnt;
; #pragma unroll
;                     for (int j = 0; j < 8; ++j) m[r][c][j] = sum[j] * inv - z0[j]; }
.LBB0_891:
	s_andn2_b64 vcc, exec, s[14:15]
	s_cbranch_vccnz .LBB0_897
	v_min_i32_e32 v61, v57, v1
	v_cmp_lt_i32_e32 vcc, 1, v61
	v_mov_b64_e32 v[78:79], v[68:69]
	v_mov_b64_e32 v[76:77], v[70:71]
	v_mov_b64_e32 v[20:21], v[72:73]
	v_mov_b64_e32 v[18:19], v[74:75]
	s_and_saveexec_b64 s[14:15], vcc
	s_cbranch_execz .LBB0_896
	v_lshl_add_u64 v[80:81], v[54:55], 0, v[14:15]
	v_add_u32_e32 v67, -1, v61
	s_mov_b64 s[46:47], 0
	v_mov_b64_e32 v[18:19], v[74:75]
	v_mov_b64_e32 v[20:21], v[72:73]
	v_mov_b64_e32 v[76:77], v[70:71]
	v_mov_b64_e32 v[78:79], v[68:69]
	s_mov_b64 s[46:47], exec
	global_load_dwordx4 v[174:177], v[80:81], off
	v_lshl_add_u64 v[80:81], v[80:81], 0, s[54:55]
	v_cmp_le_u32_e32 vcc, 2, v67
	s_and_b64 exec, s[46:47], vcc
	s_cbranch_execz .Lpl_g_iss
	global_load_dwordx4 v[178:181], v[80:81], off
	v_lshl_add_u64 v[80:81], v[80:81], 0, s[54:55]
	v_cmp_le_u32_e32 vcc, 3, v67
	s_and_b64 exec, s[46:47], vcc
	s_cbranch_execz .Lpl_g_iss
	global_load_dwordx4 v[182:185], v[80:81], off
.Lpl_g_iss:
	s_mov_b64 exec, s[46:47]
	s_waitcnt vmcnt(0)
	v_lshlrev_b32_e32 v234, 16, v174
	v_and_b32_e32 v235, 0xffff0000, v174
	v_pk_add_f32 v[78:79], v[78:79], v[234:235]
	v_lshlrev_b32_e32 v234, 16, v175
	v_and_b32_e32 v235, 0xffff0000, v175
	v_pk_add_f32 v[76:77], v[76:77], v[234:235]
	v_lshlrev_b32_e32 v234, 16, v176
	v_and_b32_e32 v235, 0xffff0000, v176
	v_pk_add_f32 v[20:21], v[20:21], v[234:235]
	v_lshlrev_b32_e32 v234, 16, v177
	v_and_b32_e32 v235, 0xffff0000, v177
	v_pk_add_f32 v[18:19], v[18:19], v[234:235]
	v_cmp_le_u32_e32 vcc, 2, v67
	s_and_b64 exec, s[46:47], vcc
	s_cbranch_execz .Lpl_g_done
	v_lshlrev_b32_e32 v234, 16, v178
	v_and_b32_e32 v235, 0xffff0000, v178
	v_pk_add_f32 v[78:79], v[78:79], v[234:235]
	v_lshlrev_b32_e32 v234, 16, v179
	v_and_b32_e32 v235, 0xffff0000, v179
	v_pk_add_f32 v[76:77], v[76:77], v[234:235]
	v_lshlrev_b32_e32 v234, 16, v180
	v_and_b32_e32 v235, 0xffff0000, v180
	v_pk_add_f32 v[20:21], v[20:21], v[234:235]
	v_lshlrev_b32_e32 v234, 16, v181
	v_and_b32_e32 v235, 0xffff0000, v181
	v_pk_add_f32 v[18:19], v[18:19], v[234:235]
	v_cmp_le_u32_e32 vcc, 3, v67
	s_and_b64 exec, s[46:47], vcc
	s_cbranch_execz .Lpl_g_done
	v_lshlrev_b32_e32 v234, 16, v182
	v_and_b32_e32 v235, 0xffff0000, v182
	v_pk_add_f32 v[78:79], v[78:79], v[234:235]
	v_lshlrev_b32_e32 v234, 16, v183
	v_and_b32_e32 v235, 0xffff0000, v183
	v_pk_add_f32 v[76:77], v[76:77], v[234:235]
	v_lshlrev_b32_e32 v234, 16, v184
	v_and_b32_e32 v235, 0xffff0000, v184
	v_pk_add_f32 v[20:21], v[20:21], v[234:235]
	v_lshlrev_b32_e32 v234, 16, v185
	v_and_b32_e32 v235, 0xffff0000, v185
	v_pk_add_f32 v[18:19], v[18:19], v[234:235]

; __device__ __forceinline__ void unpack8(const u32x4 w, float* v) { v[0] = bflo(w.x); v[1] = bfhi(w.x); v[2] = bflo(w.y); v[3] = bfhi(w.y); v[4] = bflo(w.z); v[5] = bfhi(w.z); v[6] = bflo(w.w); v[7] = bfhi(w.w); }
; __device__ __forceinline__ void row_res(KP kp, int gpost_in, int layer, bool has_next, int wid0, int row0, int row1, int b0, int nb, int tailp, bool pooled) {
;     ...
;                 else if (pooled) { const int t = row % LL, win = 2 << (c * 2 + (lane >> 5)), cnt = (t + 1) < win ? (t + 1) : win; const bf16* zp = MX + (size_t)row * DM + c * 512 + lane * 8;
;                     float z0[8], sum[8]; unpack8(*(const u32x4*)zp, z0);
; #pragma unroll
;                     for (int j = 0; j < 8; ++j) sum[j] = z0[j];
;                     for (int d = 1; d < cnt; ++d) { float zd[8]; unpack8(*(const u32x4*)(zp - (size_t)d * DM), zd);
; #pragma unroll
;                         for (int j = 0; j < 8; ++j) sum[j] += zd[j]; }
;                     const float inv = 1.0f / (float)cnt;
; #pragma unroll
;                     for (int j = 0; j < 8; ++j) m[r][c][j] = sum[j] * inv - z0[j]; }
.LBB0_903:
	s_andn2_b64 vcc, exec, s[14:15]
	s_cbranch_vccnz .LBB0_909
	v_min_i32_e32 v57, v57, v41
	v_cmp_lt_i32_e32 vcc, 1, v57
	v_mov_b64_e32 v[88:89], v[78:79]
	v_mov_b64_e32 v[86:87], v[80:81]
	v_mov_b64_e32 v[20:21], v[82:83]
	v_mov_b64_e32 v[16:17], v[84:85]
	s_and_saveexec_b64 s[4:5], vcc
	s_cbranch_execz .LBB0_908
	v_lshl_add_u64 v[14:15], v[58:59], 0, v[14:15]
	v_add_u32_e32 v61, -1, v57
	s_mov_b64 s[14:15], 0
	v_mov_b64_e32 v[16:17], v[84:85]
	v_mov_b64_e32 v[20:21], v[82:83]
	v_mov_b64_e32 v[86:87], v[80:81]
	v_mov_b64_e32 v[88:89], v[78:79]
	s_mov_b64 s[14:15], exec
	global_load_dwordx4 v[174:177], v[14:15], off
	v_lshl_add_u64 v[14:15], v[14:15], 0, s[54:55]
	v_cmp_le_u32_e32 vcc, 2, v61
	s_and_b64 exec, s[14:15], vcc
	s_cbranch_execz .Lpl_h_iss
	global_load_dwordx4 v[178:181], v[14:15], off
	v_lshl_add_u64 v[14:15], v[14:15], 0, s[54:55]
	v_cmp_le_u32_e32 vcc, 3, v61
	s_and_b64 exec, s[14:15], vcc
	s_cbranch_execz .Lpl_h_iss
	global_load_dwordx4 v[182:185], v[14:15], off
	v_lshl_add_u64 v[14:15], v[14:15], 0, s[54:55]
	v_cmp_le_u32_e32 vcc, 4, v61
	s_and_b64 exec, s[14:15], vcc
	s_cbranch_execz .Lpl_h_iss
	global_load_dwordx4 v[186:189], v[14:15], off
	v_lshl_add_u64 v[14:15], v[14:15], 0, s[54:55]
	v_cmp_le_u32_e32 vcc, 5, v61
	s_and_b64 exec, s[14:15], vcc
	s_cbranch_execz .Lpl_h_iss
	global_load_dwordx4 v[190:193], v[14:15], off
	v_lshl_add_u64 v[14:15], v[14:15], 0, s[54:55]
	v_cmp_le_u32_e32 vcc, 6, v61
	s_and_b64 exec, s[14:15], vcc
	s_cbranch_execz .Lpl_h_iss
	global_load_dwordx4 v[194:197], v[14:15], off
	v_lshl_add_u64 v[14:15], v[14:15], 0, s[54:55]
	v_cmp_le_u32_e32 vcc, 7, v61
	s_and_b64 exec, s[14:15], vcc
	s_cbranch_execz .Lpl_h_iss
	global_load_dwordx4 v[198:201], v[14:15], off
	v_lshl_add_u64 v[14:15], v[14:15], 0, s[54:55]
	v_cmp_le_u32_e32 vcc, 8, v61
	s_and_b64 exec, s[14:15], vcc
	s_cbranch_execz .Lpl_h_iss
	global_load_dwordx4 v[202:205], v[14:15], off
	v_lshl_add_u64 v[14:15], v[14:15], 0, s[54:55]
	v_cmp_le_u32_e32 vcc, 9, v61
	s_and_b64 exec, s[14:15], vcc
	s_cbranch_execz .Lpl_h_iss
	global_load_dwordx4 v[206:209], v[14:15], off
	v_lshl_add_u64 v[14:15], v[14:15], 0, s[54:55]
	v_cmp_le_u32_e32 vcc, 10, v61
	s_and_b64 exec, s[14:15], vcc
	s_cbranch_execz .Lpl_h_iss
	global_load_dwordx4 v[210:213], v[14:15], off
	v_lshl_add_u64 v[14:15], v[14:15], 0, s[54:55]
	v_cmp_le_u32_e32 vcc, 11, v61
	s_and_b64 exec, s[14:15], vcc
	s_cbranch_execz .Lpl_h_iss
	global_load_dwordx4 v[214:217], v[14:15], off
	v_lshl_add_u64 v[14:15], v[14:15], 0, s[54:55]
	v_cmp_le_u32_e32 vcc, 12, v61
	s_and_b64 exec, s[14:15], vcc
	s_cbranch_execz .Lpl_h_iss
	global_load_dwordx4 v[218:221], v[14:15], off
	v_lshl_add_u64 v[14:15], v[14:15], 0, s[54:55]
	v_cmp_le_u32_e32 vcc, 13, v61
	s_and_b64 exec, s[14:15], vcc
	s_cbranch_execz .Lpl_h_iss
	global_load_dwordx4 v[222:225], v[14:15], off
	v_lshl_add_u64 v[14:15], v[14:15], 0, s[54:55]
	v_cmp_le_u32_e32 vcc, 14, v61
	s_and_b64 exec, s[14:15], vcc
	s_cbranch_execz .Lpl_h_iss
	global_load_dwordx4 v[226:229], v[14:15], off
	v_lshl_add_u64 v[14:15], v[14:15], 0, s[54:55]
	v_cmp_le_u32_e32 vcc, 15, v61
	s_and_b64 exec, s[14:15], vcc
	s_cbranch_execz .Lpl_h_iss
	global_load_dwordx4 v[230:233], v[14:15], off
.Lpl_h_iss:
	s_mov_b64 exec, s[14:15]
	s_waitcnt vmcnt(0)
	v_lshlrev_b32_e32 v234, 16, v174
	v_and_b32_e32 v235, 0xffff0000, v174
	v_pk_add_f32 v[88:89], v[88:89], v[234:235]
	v_lshlrev_b32_e32 v234, 16, v175
	v_and_b32_e32 v235, 0xffff0000, v175
	v_pk_add_f32 v[86:87], v[86:87], v[234:235]
	v_lshlrev_b32_e32 v234, 16, v176
	v_and_b32_e32 v235, 0xffff0000, v176
	v_pk_add_f32 v[20:21], v[20:21], v[234:235]
	v_lshlrev_b32_e32 v234, 16, v177
	v_and_b32_e32 v235, 0xffff0000, v177
	v_pk_add_f32 v[16:17], v[16:17], v[234:235]
	v_cmp_le_u32_e32 vcc, 2, v61
	s_and_b64 exec, s[14:15], vcc
	s_cbranch_execz .Lpl_h_done
	v_lshlrev_b32_e32 v234, 16, v178
	v_and_b32_e32 v235, 0xffff0000, v178
	v_pk_add_f32 v[88:89], v[88:89], v[234:235]
	v_lshlrev_b32_e32 v234, 16, v179
	v_and_b32_e32 v235, 0xffff0000, v179
	v_pk_add_f32 v[86:87], v[86:87], v[234:235]
	v_lshlrev_b32_e32 v234, 16, v180
	v_and_b32_e32 v235, 0xffff0000, v180
	v_pk_add_f32 v[20:21], v[20:21], v[234:235]
	v_lshlrev_b32_e32 v234, 16, v181
	v_and_b32_e32 v235, 0xffff0000, v181
	v_pk_add_f32 v[16:17], v[16:17], v[234:235]
	v_cmp_le_u32_e32 vcc, 3, v61
	s_and_b64 exec, s[14:15], vcc
	s_cbranch_execz .Lpl_h_done
	v_lshlrev_b32_e32 v234, 16, v182
	v_and_b32_e32 v235, 0xffff0000, v182
	v_pk_add_f32 v[88:89], v[88:89], v[234:235]
	v_lshlrev_b32_e32 v234, 16, v183
	v_and_b32_e32 v235, 0xffff0000, v183
	v_pk_add_f32 v[86:87], v[86:87], v[234:235]
	v_lshlrev_b32_e32 v234, 16, v184
	v_and_b32_e32 v235, 0xffff0000, v184
	v_pk_add_f32 v[20:21], v[20:21], v[234:235]
	v_lshlrev_b32_e32 v234, 16, v185
	v_and_b32_e32 v235, 0xffff0000, v185
	v_pk_add_f32 v[16:17], v[16:17], v[234:235]
	v_cmp_le_u32_e32 vcc, 4, v61
	s_and_b64 exec, s[14:15], vcc
	s_cbranch_execz .Lpl_h_done
	v_lshlrev_b32_e32 v234, 16, v186
	v_and_b32_e32 v235, 0xffff0000, v186
	v_pk_add_f32 v[88:89], v[88:89], v[234:235]
	v_lshlrev_b32_e32 v234, 16, v187
	v_and_b32_e32 v235, 0xffff0000, v187
	v_pk_add_f32 v[86:87], v[86:87], v[234:235]
	v_lshlrev_b32_e32 v234, 16, v188
	v_and_b32_e32 v235, 0xffff0000, v188
	v_pk_add_f32 v[20:21], v[20:21], v[234:235]
	v_lshlrev_b32_e32 v234, 16, v189
	v_and_b32_e32 v235, 0xffff0000, v189
	v_pk_add_f32 v[16:17], v[16:17], v[234:235]
	v_cmp_le_u32_e32 vcc, 5, v61
	s_and_b64 exec, s[14:15], vcc
	s_cbranch_execz .Lpl_h_done
; __device__ __forceinline__ void unpack8(const u32x4 w, float* v) { v[0] = bflo(w.x); v[1] = bfhi(w.x); v[2] = bflo(w.y); v[3] = bfhi(w.y); v[4] = bflo(w.z); v[5] = bfhi(w.z); v[6] = bflo(w.w); v[7] = bfhi(w.w); }
; __device__ __forceinline__ void row_res(KP kp, int gpost_in, int layer, bool has_next, int wid0, int row0, int row1, int b0, int nb, int tailp, bool pooled) {
;     ...
;                 else if (pooled) { const int t = row % LL, win = 2 << (c * 2 + (lane >> 5)), cnt = (t + 1) < win ? (t + 1) : win; const bf16* zp = MX + (size_t)row * DM + c * 512 + lane * 8;
;                     float z0[8], sum[8]; unpack8(*(const u32x4*)zp, z0);
; #pragma unroll
;                     for (int j = 0; j < 8; ++j) sum[j] = z0[j];
;                     for (int d = 1; d < cnt; ++d) { float zd[8]; unpack8(*(const u32x4*)(zp - (size_t)d * DM), zd);
; #pragma unroll
;                         for (int j = 0; j < 8; ++j) sum[j] += zd[j]; }
;                     const float inv = 1.0f / (float)cnt;
; #pragma unroll
;                     for (int j = 0; j < 8; ++j) m[r][c][j] = sum[j] * inv - z0[j]; }
	v_lshlrev_b32_e32 v234, 16, v190
	v_and_b32_e32 v235, 0xffff0000, v190
	v_pk_add_f32 v[88:89], v[88:89], v[234:235]
	v_lshlrev_b32_e32 v234, 16, v191
	v_and_b32_e32 v235, 0xffff0000, v191
	v_pk_add_f32 v[86:87], v[86:87], v[234:235]
	v_lshlrev_b32_e32 v234, 16, v192
	v_and_b32_e32 v235, 0xffff0000, v192
	v_pk_add_f32 v[20:21], v[20:21], v[234:235]
	v_lshlrev_b32_e32 v234, 16, v193
	v_and_b32_e32 v235, 0xffff0000, v193
	v_pk_add_f32 v[16:17], v[16:17], v[234:235]
	v_cmp_le_u32_e32 vcc, 6, v61
	s_and_b64 exec, s[14:15], vcc
	s_cbranch_execz .Lpl_h_done
	v_lshlrev_b32_e32 v234, 16, v194
	v_and_b32_e32 v235, 0xffff0000, v194
	v_pk_add_f32 v[88:89], v[88:89], v[234:235]
	v_lshlrev_b32_e32 v234, 16, v195
	v_and_b32_e32 v235, 0xffff0000, v195
	v_pk_add_f32 v[86:87], v[86:87], v[234:235]
	v_lshlrev_b32_e32 v234, 16, v196
	v_and_b32_e32 v235, 0xffff0000, v196
	v_pk_add_f32 v[20:21], v[20:21], v[234:235]
	v_lshlrev_b32_e32 v234, 16, v197
	v_and_b32_e32 v235, 0xffff0000, v197
	v_pk_add_f32 v[16:17], v[16:17], v[234:235]
	v_cmp_le_u32_e32 vcc, 7, v61
	s_and_b64 exec, s[14:15], vcc
	s_cbranch_execz .Lpl_h_done
	v_lshlrev_b32_e32 v234, 16, v198
	v_and_b32_e32 v235, 0xffff0000, v198
	v_pk_add_f32 v[88:89], v[88:89], v[234:235]
	v_lshlrev_b32_e32 v234, 16, v199
	v_and_b32_e32 v235, 0xffff0000, v199
	v_pk_add_f32 v[86:87], v[86:87], v[234:235]
	v_lshlrev_b32_e32 v234, 16, v200
	v_and_b32_e32 v235, 0xffff0000, v200
	v_pk_add_f32 v[20:21], v[20:21], v[234:235]
	v_lshlrev_b32_e32 v234, 16, v201
	v_and_b32_e32 v235, 0xffff0000, v201
	v_pk_add_f32 v[16:17], v[16:17], v[234:235]
	v_cmp_le_u32_e32 vcc, 8, v61
	s_and_b64 exec, s[14:15], vcc
	s_cbranch_execz .Lpl_h_done
	v_lshlrev_b32_e32 v234, 16, v202
	v_and_b32_e32 v235, 0xffff0000, v202
	v_pk_add_f32 v[88:89], v[88:89], v[234:235]
	v_lshlrev_b32_e32 v234, 16, v203
	v_and_b32_e32 v235, 0xffff0000, v203
	v_pk_add_f32 v[86:87], v[86:87], v[234:235]
	v_lshlrev_b32_e32 v234, 16, v204
	v_and_b32_e32 v235, 0xffff0000, v204
	v_pk_add_f32 v[20:21], v[20:21], v[234:235]
	v_lshlrev_b32_e32 v234, 16, v205
	v_and_b32_e32 v235, 0xffff0000, v205
	v_pk_add_f32 v[16:17], v[16:17], v[234:235]
	v_cmp_le_u32_e32 vcc, 9, v61
	s_and_b64 exec, s[14:15], vcc
	s_cbranch_execz .Lpl_h_done
	v_lshlrev_b32_e32 v234, 16, v206
	v_and_b32_e32 v235, 0xffff0000, v206
	v_pk_add_f32 v[88:89], v[88:89], v[234:235]
	v_lshlrev_b32_e32 v234, 16, v207
	v_and_b32_e32 v235, 0xffff0000, v207
	v_pk_add_f32 v[86:87], v[86:87], v[234:235]
	v_lshlrev_b32_e32 v234, 16, v208
	v_and_b32_e32 v235, 0xffff0000, v208
	v_pk_add_f32 v[20:21], v[20:21], v[234:235]
	v_lshlrev_b32_e32 v234, 16, v209
	v_and_b32_e32 v235, 0xffff0000, v209
	v_pk_add_f32 v[16:17], v[16:17], v[234:235]
	v_cmp_le_u32_e32 vcc, 10, v61
	s_and_b64 exec, s[14:15], vcc
	s_cbranch_execz .Lpl_h_done
	v_lshlrev_b32_e32 v234, 16, v210
	v_and_b32_e32 v235, 0xffff0000, v210
	v_pk_add_f32 v[88:89], v[88:89], v[234:235]
	v_lshlrev_b32_e32 v234, 16, v211
	v_and_b32_e32 v235, 0xffff0000, v211
	v_pk_add_f32 v[86:87], v[86:87], v[234:235]
	v_lshlrev_b32_e32 v234, 16, v212
	v_and_b32_e32 v235, 0xffff0000, v212
	v_pk_add_f32 v[20:21], v[20:21], v[234:235]
	v_lshlrev_b32_e32 v234, 16, v213
	v_and_b32_e32 v235, 0xffff0000, v213
	v_pk_add_f32 v[16:17], v[16:17], v[234:235]
	v_cmp_le_u32_e32 vcc, 11, v61
	s_and_b64 exec, s[14:15], vcc
	s_cbranch_execz .Lpl_h_done
	v_lshlrev_b32_e32 v234, 16, v214
	v_and_b32_e32 v235, 0xffff0000, v214
	v_pk_add_f32 v[88:89], v[88:89], v[234:235]
	v_lshlrev_b32_e32 v234, 16, v215
	v_and_b32_e32 v235, 0xffff0000, v215
	v_pk_add_f32 v[86:87], v[86:87], v[234:235]
	v_lshlrev_b32_e32 v234, 16, v216
	v_and_b32_e32 v235, 0xffff0000, v216
	v_pk_add_f32 v[20:21], v[20:21], v[234:235]
	v_lshlrev_b32_e32 v234, 16, v217
	v_and_b32_e32 v235, 0xffff0000, v217
	v_pk_add_f32 v[16:17], v[16:17], v[234:235]
	v_cmp_le_u32_e32 vcc, 12, v61
	s_and_b64 exec, s[14:15], vcc
	s_cbranch_execz .Lpl_h_done
	v_lshlrev_b32_e32 v234, 16, v218
	v_and_b32_e32 v235, 0xffff0000, v218
	v_pk_add_f32 v[88:89], v[88:89], v[234:235]
	v_lshlrev_b32_e32 v234, 16, v219
	v_and_b32_e32 v235, 0xffff0000, v219
	v_pk_add_f32 v[86:87], v[86:87], v[234:235]
	v_lshlrev_b32_e32 v234, 16, v220
	v_and_b32_e32 v235, 0xffff0000, v220
	v_pk_add_f32 v[20:21], v[20:21], v[234:235]
	v_lshlrev_b32_e32 v234, 16, v221
	v_and_b32_e32 v235, 0xffff0000, v221
	v_pk_add_f32 v[16:17], v[16:17], v[234:235]
	v_cmp_le_u32_e32 vcc, 13, v61
	s_and_b64 exec, s[14:15], vcc
	s_cbranch_execz .Lpl_h_done
	v_lshlrev_b32_e32 v234, 16, v222
	v_and_b32_e32 v235, 0xffff0000, v222
	v_pk_add_f32 v[88:89], v[88:89], v[234:235]
	v_lshlrev_b32_e32 v234, 16, v223
	v_and_b32_e32 v235, 0xffff0000, v223
	v_pk_add_f32 v[86:87], v[86:87], v[234:235]
	v_lshlrev_b32_e32 v234, 16, v224
	v_and_b32_e32 v235, 0xffff0000, v224
	v_pk_add_f32 v[20:21], v[20:21], v[234:235]
	v_lshlrev_b32_e32 v234, 16, v225
	v_and_b32_e32 v235, 0xffff0000, v225
	v_pk_add_f32 v[16:17], v[16:17], v[234:235]
	v_cmp_le_u32_e32 vcc, 14, v61
	s_and_b64 exec, s[14:15], vcc
	s_cbranch_execz .Lpl_h_done
	v_lshlrev_b32_e32 v234, 16, v226
	v_and_b32_e32 v235, 0xffff0000, v226
	v_pk_add_f32 v[88:89], v[88:89], v[234:235]
	v_lshlrev_b32_e32 v234, 16, v227
	v_and_b32_e32 v235, 0xffff0000, v227
	v_pk_add_f32 v[86:87], v[86:87], v[234:235]
	v_lshlrev_b32_e32 v234, 16, v228
	v_and_b32_e32 v235, 0xffff0000, v228
	v_pk_add_f32 v[20:21], v[20:21], v[234:235]
	v_lshlrev_b32_e32 v234, 16, v229
	v_and_b32_e32 v235, 0xffff0000, v229
	v_pk_add_f32 v[16:17], v[16:17], v[234:235]
	v_cmp_le_u32_e32 vcc, 15, v61
	s_and_b64 exec, s[14:15], vcc
	s_cbranch_execz .Lpl_h_done
	v_lshlrev_b32_e32 v234, 16, v230
	v_and_b32_e32 v235, 0xffff0000, v230
	v_pk_add_f32 v[88:89], v[88:89], v[234:235]
	v_lshlrev_b32_e32 v234, 16, v231
	v_and_b32_e32 v235, 0xffff0000, v231
	v_pk_add_f32 v[86:87], v[86:87], v[234:235]
	v_lshlrev_b32_e32 v234, 16, v232
	v_and_b32_e32 v235, 0xffff0000, v232
	v_pk_add_f32 v[20:21], v[20:21], v[234:235]
	v_lshlrev_b32_e32 v234, 16, v233
	v_and_b32_e32 v235, 0xffff0000, v233
	v_pk_add_f32 v[16:17], v[16:17], v[234:235]
.Lpl_h_done:
	s_mov_b64 exec, s[14:15]
.LBB0_908:
	s_or_b64 exec, exec, s[4:5]
	v_cvt_f32_i32_e32 v14, v57
	v_div_scale_f32 v15, s[4:5], v14, v14, 1.0
	v_rcp_f32_e32 v57, v15
	v_div_scale_f32 v61, vcc, 1.0, v14, 1.0
	v_fma_f32 v67, -v15, v57, 1.0
	v_fmac_f32_e32 v57, v67, v57
	v_mul_f32_e32 v67, v61, v57
	v_fma_f32 v90, -v15, v67, v61
	v_fmac_f32_e32 v67, v90, v57
	v_fma_f32 v15, -v15, v67, v61
	v_div_fmas_f32 v15, v15, v57, v67
	v_div_fixup_f32 v14, v15, v14, 1.0
	v_pk_fma_f32 v[78:79], v[14:15], v[88:89], v[78:79] op_sel_hi:[0,1,1] neg_lo:[0,0,1] neg_hi:[0,0,1]
	v_pk_fma_f32 v[80:81], v[14:15], v[86:87], v[80:81] op_sel_hi:[0,1,1] neg_lo:[0,0,1] neg_hi:[0,0,1]
	v_pk_fma_f32 v[82:83], v[14:15], v[20:21], v[82:83] op_sel_hi:[0,1,1] neg_lo:[0,0,1] neg_hi:[0,0,1]
	v_pk_fma_f32 v[84:85], v[14:15], v[16:17], v[84:85] op_sel_hi:[0,1,1] neg_lo:[0,0,1] neg_hi:[0,0,1]
